# XCD-local barrier (census-verified placement) for mixer->w_out GEMM and w_down GEMM->next w_in GEMM seams
# speedup vs baseline: 1.0151x; 1.0151x over previous
; #define LAS __attribute__((address_space(3)))
; __device__ __forceinline__ unsigned xb_add(unsigned* p, unsigned v) { return __hip_atomic_fetch_add(p, v, __ATOMIC_RELAXED, __HIP_MEMORY_SCOPE_AGENT); }
; __device__ __forceinline__ unsigned xb_xcc_id() { return (unsigned)__builtin_amdgcn_s_getreg((3 << 11) | 20) & 0xFu; }
; __device__ __forceinline__ XcdBarrier xcd_barrier_post(unsigned* bar, volatile LAS unsigned* st) {
;     XcdBarrier b; b.bar = bar; b.x = xb_xcc_id(); b.st = st;
;     if (threadIdx.x == 0) (void)xb_add(&bar[XB_XCNT(b.x)], 1u);
;     return b;
; __global__ void __launch_bounds__(NTHR, 2) hybrid_fwd(Args args) {
;     ...
;     if (threadIdx.x < 16) MISC[threadIdx.x] = 0u;
;     if (threadIdx.x == 0) {
;     ...
;         PUTP(0) PUTP(1) PUTP(2) PUTP(3) PUTP(4) PUTP(5) PUTP(6) PUTP(7) PUTP(8) PUTP(9) PUTP(10) PUTP(11) PUTP(12) PUTP(13)
;     ...
;     }
;     __syncthreads();
;     XcdBarrier xbar = xcd_barrier_post((unsigned*)(args.ws + WS_BAR), MISC);
_Z10hybrid_fwd4Args:
	s_mov_b32 s27, s2
	s_mov_b32 s101, 0
	s_load_dword s2, s[0:1], 0x88
	s_load_dwordx2 s[96:97], s[0:1], 0x80
	s_add_u32 s4, s0, 0x80
	s_addc_u32 s5, s1, 0
	v_and_b32_e32 v218, 0x3ff, v0
	v_writelane_b32 v252, s4, 0
	v_cmp_gt_u32_e32 vcc, 16, v218
	s_nop 0
	v_writelane_b32 v252, s5, 1
	s_and_saveexec_b64 s[4:5], vcc
	v_lshl_add_u32 v1, v218, 2, 0
	v_add_u32_e32 v1, 0x23fc0, v1
	v_mov_b32_e32 v2, 0
	ds_write_b32 v1, v2
	s_or_b64 exec, exec, s[4:5]
	s_load_dwordx16 s[36:51], s[0:1], 0x40
	v_cmp_eq_u32_e64 s[86:87], 0, v218
	s_and_saveexec_b64 s[20:21], s[86:87]
	s_cbranch_execz .LBB0_4
	s_load_dwordx16 s[4:19], s[0:1], 0x0
	s_add_i32 s0, 0, 0x23f00
	s_add_i32 s1, 0, 0x23f04
	v_mov_b32_e32 v1, s0
	v_mov_b32_e32 v2, s1
	s_waitcnt lgkmcnt(0)
	v_mov_b32_e32 v3, s4
	ds_write_b32 v1, v3
	v_mov_b32_e32 v1, s5
	s_add_i32 s0, 0, 0x23f08
	ds_write_b32 v2, v1
	v_mov_b32_e32 v1, s0
	v_mov_b32_e32 v2, s6
	s_add_i32 s0, 0, 0x23f0c
	ds_write_b32 v1, v2
	v_mov_b32_e32 v1, s0
	v_mov_b32_e32 v2, s7
	s_add_i32 s0, 0, 0x23f10
	ds_write_b32 v1, v2
	v_mov_b32_e32 v1, s0
	v_mov_b32_e32 v2, s8
	s_add_i32 s0, 0, 0x23f14
	ds_write_b32 v1, v2
	v_mov_b32_e32 v1, s0
	v_mov_b32_e32 v2, s9
	s_add_i32 s0, 0, 0x23f18
	ds_write_b32 v1, v2
	v_mov_b32_e32 v1, s0
	v_mov_b32_e32 v2, s10
	s_add_i32 s0, 0, 0x23f1c
	ds_write_b32 v1, v2
	v_mov_b32_e32 v1, s0
	v_mov_b32_e32 v2, s11
	s_add_i32 s0, 0, 0x23f20
	ds_write_b32 v1, v2
	v_mov_b32_e32 v1, s0
	v_mov_b32_e32 v2, s12
	s_add_i32 s0, 0, 0x23f24
	ds_write_b32 v1, v2
	v_mov_b32_e32 v1, s0
	v_mov_b32_e32 v2, s13
	s_add_i32 s0, 0, 0x23f28
	ds_write_b32 v1, v2
	v_mov_b32_e32 v1, s0
	v_mov_b32_e32 v2, s14
	s_add_i32 s0, 0, 0x23f2c
	ds_write_b32 v1, v2
	v_mov_b32_e32 v1, s0
	v_mov_b32_e32 v2, s15
	s_add_i32 s0, 0, 0x23f30
	ds_write_b32 v1, v2
	v_mov_b32_e32 v1, s0
	v_mov_b32_e32 v2, s16
	s_add_i32 s0, 0, 0x23f34
	ds_write_b32 v1, v2
	v_mov_b32_e32 v1, s0
	v_mov_b32_e32 v2, s17
	s_add_i32 s0, 0, 0x23f38
	ds_write_b32 v1, v2
	v_mov_b32_e32 v1, s0
	v_mov_b32_e32 v2, s18
	s_add_i32 s0, 0, 0x23f3c
	ds_write_b32 v1, v2
	v_mov_b32_e32 v1, s0
	v_mov_b32_e32 v2, s19
	s_add_i32 s0, 0, 0x23f40
	ds_write_b32 v1, v2
	v_mov_b32_e32 v1, s0
	v_mov_b32_e32 v2, s36
	s_add_i32 s0, 0, 0x23f44
	ds_write_b32 v1, v2
	v_mov_b32_e32 v1, s0
	v_mov_b32_e32 v2, s37
	s_add_i32 s0, 0, 0x23f48
	ds_write_b32 v1, v2
	v_mov_b32_e32 v1, s0
	v_mov_b32_e32 v2, s38
	s_add_i32 s0, 0, 0x23f4c
	ds_write_b32 v1, v2
	v_mov_b32_e32 v1, s0
	v_mov_b32_e32 v2, s39
	s_add_i32 s0, 0, 0x23f50
	ds_write_b32 v1, v2
	v_mov_b32_e32 v1, s0
	v_mov_b32_e32 v2, s40
	s_add_i32 s0, 0, 0x23f54
	ds_write_b32 v1, v2
	v_mov_b32_e32 v1, s0
	v_mov_b32_e32 v2, s41
	s_add_i32 s0, 0, 0x23f58
	ds_write_b32 v1, v2
	v_mov_b32_e32 v1, s0
	v_mov_b32_e32 v2, s42
	s_add_i32 s0, 0, 0x23f5c
	ds_write_b32 v1, v2
	v_mov_b32_e32 v1, s0
	v_mov_b32_e32 v2, s43
	s_add_i32 s0, 0, 0x23f60
	ds_write_b32 v1, v2
	v_mov_b32_e32 v1, s0
	v_mov_b32_e32 v2, s44
	s_add_i32 s0, 0, 0x23f64
	ds_write_b32 v1, v2
	v_mov_b32_e32 v1, s0
	v_mov_b32_e32 v2, s45
	s_add_i32 s0, 0, 0x23f68
	ds_write_b32 v1, v2
	v_mov_b32_e32 v1, s0
	v_mov_b32_e32 v2, s46
	s_add_i32 s0, 0, 0x23f6c
	ds_write_b32 v1, v2
	v_mov_b32_e32 v1, s0
	v_mov_b32_e32 v2, s47
	ds_write_b32 v1, v2
.LBB0_4:
	s_or_b64 exec, exec, s[20:21]
	s_waitcnt lgkmcnt(0)
	s_barrier
	s_add_u32 s6, s50, 0x6200000
	s_getreg_b32 s0, hwreg(HW_REG_XCC_ID, 0, 4)
	s_addc_u32 s7, s51, 0
	s_and_b32 s12, s0, 15
	s_lshl_b32 s11, s12, 6
	s_and_saveexec_b64 s[0:1], s[86:87]
	s_cbranch_execz .LBB0_7
	s_mov_b64 s[4:5], exec
	v_mbcnt_lo_u32_b32 v1, s4, 0
	v_mbcnt_hi_u32_b32 v1, s5, v1
	v_cmp_eq_u32_e32 vcc, 0, v1
	s_and_b64 s[8:9], exec, vcc
	s_mov_b64 exec, s[8:9]
	s_cbranch_execz .LBB0_7
	s_lshl_b32 s3, s11, 2
	s_bcnt1_i32_b64 s4, s[4:5]
	v_mov_b32_e32 v1, s3
	v_mov_b32_e32 v2, s4
	s_and_b32 s8, s27, 7
	s_lshl_b32 s8, 1, s8
	v_mov_b32_e32 v3, s8
	global_atomic_or v1, v3, s[6:7] offset:1028
	s_waitcnt vmcnt(0)
	global_atomic_add v1, v2, s[6:7] offset:1024

; __device__ __forceinline__ void xcd_barrier(const XcdBarrier& b) {
;     asm volatile("s_waitcnt vmcnt(0)" ::: "memory");
;     __syncthreads();
;     if (threadIdx.x == 0) {
;         unsigned* bar = b.bar;
;         __builtin_amdgcn_s_waitcnt(0);
;         unsigned nloc = b.st[0], nx = b.st[1];
;         if (nloc == 0u) { xcd_barrier_complete(bar, b.x, nloc, nx); b.st[0] = nloc; b.st[1] = nx; }
.LBB0_362:
	s_waitcnt vmcnt(0)
	s_waitcnt vmcnt(0) lgkmcnt(0)
	s_barrier
	s_and_saveexec_b64 s[0:1], s[86:87]
	s_cbranch_execz .LBB0_9
	s_cmp_gt_u32 s97, 1
	s_cbranch_scc1 .Lxl_flag_done
	v_readlane_b32 s6, v254, 40
	v_readlane_b32 s7, v254, 41
	s_cmp_lg_u32 s97, 0
	s_cbranch_scc1 .Lxl_chk_done
	s_getreg_b32 s2, hwreg(HW_REG_XCC_ID, 0, 4)
	s_lshl_b32 s2, s2, 8
	v_mov_b32_e32 v20, s2
	s_nop 4
	global_load_dwordx2 v[22:23], v20, s[6:7] offset:512 sc1
	s_and_b32 s2, s27, 7
	s_lshl_b32 s2, 1, s2
	s_waitcnt vmcnt(0)
	v_readfirstlane_b32 s8, v22
	v_readfirstlane_b32 s9, v23
	s_nop 3
	s_cmp_lg_u32 s8, 32
	s_cbranch_scc1 .Lxl_bad
	s_cmp_lg_u32 s9, s2
	s_cbranch_scc1 .Lxl_bad
	s_cmp_eq_u32 s96, 0x100
	s_cbranch_scc1 .Lxl_chk_done
.Lxl_bad:
	v_mov_b32_e32 v20, 1
	global_atomic_add v193, v20, s[6:7] offset:4
	s_waitcnt vmcnt(0)
.Lxl_chk_done:
	s_cmp_lg_u32 s97, 1
	s_cbranch_scc1 .Lxl_flag_done
	s_nop 4
	global_load_dword v20, v193, s[6:7] offset:4 sc1
	s_waitcnt vmcnt(0)
	v_readfirstlane_b32 s2, v20
	s_nop 3
	s_cmp_eq_u32 s2, 0
	s_cselect_b32 s101, 1, 0
.Lxl_flag_done:
	v_readlane_b32 s2, v254, 28
	s_waitcnt vmcnt(0) expcnt(0) lgkmcnt(0)
	s_nop 0
	v_mov_b32_e32 v0, s2
	ds_read_b32 v2, v0
	v_readlane_b32 s2, v254, 29
	s_waitcnt lgkmcnt(0)
	v_cmp_ne_u32_e32 vcc, 0, v2
	v_mov_b32_e32 v0, s2
	ds_read_b32 v0, v0
	s_cbranch_vccnz .LBB0_378
	s_mov_b32 s2, 1
	s_branch .LBB0_366

; __device__ __forceinline__ unsigned xb_ld(unsigned* p)              { return __hip_atomic_load(p, __ATOMIC_RELAXED, __HIP_MEMORY_SCOPE_AGENT); }
; __device__ __forceinline__ unsigned xb_add(unsigned* p, unsigned v) { return __hip_atomic_fetch_add(p, v, __ATOMIC_RELAXED, __HIP_MEMORY_SCOPE_AGENT); }
; #define XB_SPIN(cond, bar) do { unsigned _sp = 0; while (cond) { __builtin_amdgcn_s_sleep(1); \
;     if ((++_sp & 255u) == 0u) { if (xb_ld(&(bar)[XB_TMO])) break; if (_sp > XB_SPIN_CAP) { atomicAdd(&(bar)[XB_TMO], 1u); break; } } } } while (0)
; __device__ __forceinline__ void xcd_barrier(const XcdBarrier& b) {
;     ...
;         const unsigned old = xb_add(&bar[XB_XSUB(b.x)], 1u);
;         const unsigned gen = old / nloc;
;         if (old + 1u == (gen + 1u) * nloc) {
;             __builtin_amdgcn_fence(__ATOMIC_RELEASE, "agent");
;             asm volatile("s_waitcnt vmcnt(0)" ::: "memory");
;             const unsigned og = xb_add(&bar[XB_TOP], 1u);
;             const unsigned tg = og / nx;
;             if (og + 1u == (tg + 1u) * nx) xb_add(&bar[XB_TOPGEN], 1u);
;             else XB_SPIN(xb_ld(&bar[XB_TOPGEN]) == tg, bar);
.LBB0_394:
	s_andn2_saveexec_b64 s[6:7], s[6:7]
	s_cbranch_execz .LBB0_9
	s_mov_b64 s[6:7], exec
	s_waitcnt lgkmcnt(0)
	s_cmp_eq_u32 s101, 0
	s_cbranch_scc1 .Lxl_global
	s_cmp_lt_i32 s97, 1
	s_cbranch_scc1 .Lxl_global
	s_mul_i32 s2, s97, 0xcd
	s_lshr_b32 s2, s2, 10
	s_mul_i32 s2, s2, 5
	s_sub_i32 s2, s97, s2
	s_cmp_eq_u32 s2, 1
	s_cbranch_scc1 .Lxl_release
	s_cmp_lg_u32 s2, 4
	s_cbranch_scc1 .Lxl_global
	s_cmp_lg_u32 s97, 19
	s_cbranch_scc1 .Lxl_release
.Lxl_global:
	buffer_wbl2 sc1
	s_waitcnt lgkmcnt(0)
	s_waitcnt vmcnt(0)
	v_mbcnt_lo_u32_b32 v1, s6, 0
	v_mbcnt_hi_u32_b32 v1, s7, v1
	v_cmp_eq_u32_e32 vcc, 0, v1
	s_and_saveexec_b64 s[8:9], vcc
	s_cbranch_execz .LBB0_397
	s_bcnt1_i32_b64 s2, s[6:7]
	v_readlane_b32 s6, v253, 24
	v_mov_b32_e32 v2, s2
	v_readlane_b32 s7, v253, 25
	s_nop 4
	global_atomic_add v2, v193, v2, s[6:7] sc0

; __device__ __forceinline__ unsigned xb_add(unsigned* p, unsigned v) { return __hip_atomic_fetch_add(p, v, __ATOMIC_RELAXED, __HIP_MEMORY_SCOPE_AGENT); }
; __device__ __forceinline__ void xcd_barrier(const XcdBarrier& b) {
;     ...
;             __builtin_amdgcn_fence(__ATOMIC_ACQUIRE, "agent");
;             xb_add(&bar[XB_XGEN(b.x)], 1u);
;             asm volatile("s_waitcnt vmcnt(0)" ::: "memory");
.Lxl_release:
	s_mov_b64 s[6:7], exec
	v_mbcnt_lo_u32_b32 v0, s6, 0
	v_mbcnt_hi_u32_b32 v0, s7, v0
	v_cmp_eq_u32_e32 vcc, 0, v0
	s_waitcnt vmcnt(0)
	s_and_saveexec_b64 s[8:9], vcc
	s_cbranch_execz .LBB0_8
	s_bcnt1_i32_b64 s2, s[6:7]
	v_readlane_b32 s6, v253, 22
	v_mov_b32_e32 v0, s2
	v_readlane_b32 s7, v253, 23
	s_nop 4
	global_atomic_add v193, v0, s[6:7]
	s_branch .LBB0_8
